# final RMSNorm loop: cross-row prefetch -- next row's chunk j (pointer clamped to the current row past the end) loaded right behind the store of chunk j, peeled first row with exact counted waits (8+j)
# baseline (speedup 1.0000x reference)
; __device__ __forceinline__ void final_phase(float* x, const float* ssq, const float* gn, bool team) {
;     const int tid = threadIdx.x, lane = tid & 63, wave = tid >> 6; const int gw = blockIdx.x * 8 + wave, NGW = gridDim.x * 8;
;     const int mbeg = team ? my_pm() * 256 + (int)(blockIdx.x >> 6) * 64 + wave : gw, mend = team ? my_pm() * 256 + (int)(blockIdx.x >> 6) * 64 + 64 : M, mstep = team ? 8 : NGW;
;     for (int m = mbeg; m < mend; m += mstep) { float s = ssq[(size_t)m * 32 + (lane & 31)];
; #pragma unroll
;         for (int o = 1; o < 32; o <<= 1) s += __shfl_xor(s, o);
;         const float rs = __builtin_amdgcn_rsqf(s * (1.0f / D) + 1e-6f); f32x4* xr = (f32x4*)(x + (size_t)m * D) + lane; const f32x4* gr = (const f32x4*)gn + lane;
; #pragma unroll
;         for (int j = 0; j < 8; ++j) xr[64 * j] = xr[64 * j] * rs * gr[64 * j]; }
.LBB0_2362:
	v_add_u32_e32 v1, v3, v4
	v_add_u32_e32 v1, 64, v1
	v_mov_b32_e32 v3, 0x4000
	s_waitcnt vmcnt(19)
	v_cndmask_b32_e64 v22, v3, v1, s[88:89]
	v_cmp_lt_i32_e32 vcc, v0, v22
	s_and_saveexec_b64 s[0:1], vcc
	s_cbranch_execz .LBB0_2365
	v_mbcnt_lo_u32_b32 v3, -1, 0
	v_mbcnt_hi_u32_b32 v3, -1, v3
	v_and_b32_e32 v1, 63, v200
	v_and_b32_e32 v4, 64, v3
	v_add_u32_e32 v6, 64, v4
	v_lshlrev_b32_e32 v14, 4, v1
	v_xor_b32_e32 v1, 1, v3
	v_cmp_lt_i32_e32 vcc, v1, v6
	s_load_dwordx4 s[4:7], s[92:93], 0xe8
	v_mov_b32_e32 v15, 0
	v_cndmask_b32_e32 v1, v3, v1, vcc
	v_lshlrev_b32_e32 v23, 2, v1
	v_xor_b32_e32 v1, 2, v3
	v_cmp_lt_i32_e32 vcc, v1, v6
	v_and_b32_e32 v20, 31, v200
	s_waitcnt lgkmcnt(0)
	v_lshl_add_u64 v[4:5], s[4:5], 0, v[14:15]
	v_cndmask_b32_e32 v1, v3, v1, vcc
	v_lshlrev_b32_e32 v24, 2, v1
	v_xor_b32_e32 v1, 4, v3
	v_cmp_lt_i32_e32 vcc, v1, v6
	s_mov_b64 s[2:3], 0x1400
	s_mov_b64 s[0:1], 0x1000
	v_cndmask_b32_e32 v1, v3, v1, vcc
	v_lshlrev_b32_e32 v25, 2, v1
	v_xor_b32_e32 v1, 8, v3
	v_cmp_lt_i32_e32 vcc, v1, v6
	v_lshl_add_u64 v[8:9], v[4:5], 0, s[2:3]
	s_mov_b64 s[2:3], 0x1800
	v_cndmask_b32_e32 v1, v3, v1, vcc
	s_waitcnt vmcnt(18)
	v_lshlrev_b32_e32 v26, 2, v1
	v_xor_b32_e32 v1, 16, v3
	v_cmp_lt_i32_e32 vcc, v1, v6
	v_lshl_add_u64 v[6:7], v[4:5], 0, s[0:1]
	v_lshl_add_u64 v[10:11], v[4:5], 0, s[2:3]
	v_cndmask_b32_e32 v1, v3, v1, vcc
	v_lshlrev_b32_e32 v27, 2, v1
	v_ashrrev_i32_e32 v1, 31, v0
	v_lshlrev_b64 v[16:17], 13, v[0:1]
	v_or_b32_e32 v16, v16, v14
	v_lshlrev_b64 v[18:19], 7, v[0:1]
	v_lshl_add_u64 v[14:15], s[6:7], 0, v[16:17]
	v_lshl_or_b32 v18, v20, 2, v18
	s_mov_b64 s[2:3], 0x1c00
	v_lshl_add_u64 v[14:15], v[14:15], 0, s[0:1]
	v_ashrrev_i32_e32 v3, 31, v2
	v_lshl_add_u64 v[18:19], s[74:75], 0, v[18:19]
	s_mov_b64 s[0:1], 0x200000
	v_lshl_add_u64 v[12:13], v[4:5], 0, s[2:3]
	v_lshlrev_b64 v[16:17], 13, v[2:3]
	v_lshl_add_u64 v[18:19], v[18:19], 0, s[0:1]
	v_lshlrev_b64 v[20:21], 7, v[2:3]
	s_mov_b64 s[0:1], 0
	v_mov_b32_e32 v1, 0x358637bd
	global_load_dwordx4 v[44:47], v[4:5], off
	global_load_dwordx4 v[48:51], v[4:5], off offset:1024
	global_load_dwordx4 v[52:55], v[4:5], off offset:2048
	global_load_dwordx4 v[56:59], v[4:5], off offset:3072
	global_load_dwordx4 v[60:63], v[6:7], off
	global_load_dwordx4 v[64:67], v[8:9], off
	global_load_dwordx4 v[68:71], v[10:11], off
	global_load_dwordx4 v[72:75], v[12:13], off
	global_load_dword v3, v[18:19], off
	global_load_dwordx4 v[76:79], v[14:15], off offset:-4096
	global_load_dwordx4 v[80:83], v[14:15], off offset:-3072
	global_load_dwordx4 v[84:87], v[14:15], off offset:-2048
	global_load_dwordx4 v[88:91], v[14:15], off offset:-1024
	global_load_dwordx4 v[92:95], v[14:15], off
	global_load_dwordx4 v[96:99], v[14:15], off offset:1024
	global_load_dwordx4 v[100:103], v[14:15], off offset:2048
	global_load_dwordx4 v[104:107], v[14:15], off offset:3072
	v_add_u32_e32 v0, v0, v2
	v_cmp_ge_i32_e32 vcc, v0, v22
	s_or_b64 s[0:1], vcc, s[0:1]
	s_nop 1
	v_cndmask_b32_e64 v108, v16, 0, vcc
	v_cndmask_b32_e64 v109, v17, 0, vcc
	v_cndmask_b32_e64 v112, v20, 0, vcc
	v_cndmask_b32_e64 v113, v21, 0, vcc
	v_lshl_add_u64 v[110:111], v[14:15], 0, v[108:109]
	v_lshl_add_u64 v[18:19], v[18:19], 0, v[112:113]
	s_waitcnt vmcnt(8)
	v_mov_b32_e32 v42, v3
	global_load_dword v3, v[18:19], off
	ds_bpermute_b32 v40, v23, v42
	s_waitcnt lgkmcnt(0)
	v_add_f32_e32 v42, v42, v40
	ds_bpermute_b32 v40, v24, v42
	s_waitcnt lgkmcnt(0)
	v_add_f32_e32 v42, v42, v40
	ds_bpermute_b32 v40, v25, v42
	s_waitcnt lgkmcnt(0)
	v_add_f32_e32 v42, v42, v40
	ds_bpermute_b32 v40, v26, v42
	s_waitcnt lgkmcnt(0)
	v_add_f32_e32 v42, v42, v40
	ds_bpermute_b32 v40, v27, v42
	s_waitcnt lgkmcnt(0)
	v_add_f32_e32 v42, v42, v40
	v_fmamk_f32 v42, v42, 0x3a000000, v1
	v_rsq_f32_e32 v40, v42
	s_waitcnt vmcnt(8)
	v_pk_mul_f32 v[76:77], v[76:77], v[40:41] op_sel_hi:[1,0]
	v_pk_mul_f32 v[78:79], v[78:79], v[40:41] op_sel_hi:[1,0]
	v_pk_mul_f32 v[76:77], v[44:45], v[76:77]
	v_pk_mul_f32 v[78:79], v[46:47], v[78:79]
	global_store_dwordx4 v[14:15], v[76:79], off offset:-4096
	global_load_dwordx4 v[76:79], v[110:111], off offset:-4096
	s_waitcnt vmcnt(9)
	v_pk_mul_f32 v[80:81], v[80:81], v[40:41] op_sel_hi:[1,0]
	v_pk_mul_f32 v[82:83], v[82:83], v[40:41] op_sel_hi:[1,0]
	v_pk_mul_f32 v[80:81], v[48:49], v[80:81]
	v_pk_mul_f32 v[82:83], v[50:51], v[82:83]
	global_store_dwordx4 v[14:15], v[80:83], off offset:-3072
	global_load_dwordx4 v[80:83], v[110:111], off offset:-3072
	s_waitcnt vmcnt(10)
	v_pk_mul_f32 v[84:85], v[84:85], v[40:41] op_sel_hi:[1,0]
	v_pk_mul_f32 v[86:87], v[86:87], v[40:41] op_sel_hi:[1,0]
	v_pk_mul_f32 v[84:85], v[52:53], v[84:85]
	v_pk_mul_f32 v[86:87], v[54:55], v[86:87]
	global_store_dwordx4 v[14:15], v[84:87], off offset:-2048
	global_load_dwordx4 v[84:87], v[110:111], off offset:-2048
	s_waitcnt vmcnt(11)
	v_pk_mul_f32 v[88:89], v[88:89], v[40:41] op_sel_hi:[1,0]
	v_pk_mul_f32 v[90:91], v[90:91], v[40:41] op_sel_hi:[1,0]
	v_pk_mul_f32 v[88:89], v[56:57], v[88:89]
	v_pk_mul_f32 v[90:91], v[58:59], v[90:91]
	global_store_dwordx4 v[14:15], v[88:91], off offset:-1024
	global_load_dwordx4 v[88:91], v[110:111], off offset:-1024
	s_waitcnt vmcnt(12)
	v_pk_mul_f32 v[92:93], v[92:93], v[40:41] op_sel_hi:[1,0]
	v_pk_mul_f32 v[94:95], v[94:95], v[40:41] op_sel_hi:[1,0]
	v_pk_mul_f32 v[92:93], v[60:61], v[92:93]
	v_pk_mul_f32 v[94:95], v[62:63], v[94:95]
	global_store_dwordx4 v[14:15], v[92:95], off
	global_load_dwordx4 v[92:95], v[110:111], off
	s_waitcnt vmcnt(13)
	v_pk_mul_f32 v[96:97], v[96:97], v[40:41] op_sel_hi:[1,0]
	v_pk_mul_f32 v[98:99], v[98:99], v[40:41] op_sel_hi:[1,0]
	v_pk_mul_f32 v[96:97], v[64:65], v[96:97]
	v_pk_mul_f32 v[98:99], v[66:67], v[98:99]
	global_store_dwordx4 v[14:15], v[96:99], off offset:1024
	global_load_dwordx4 v[96:99], v[110:111], off offset:1024
	s_waitcnt vmcnt(14)
	v_pk_mul_f32 v[100:101], v[100:101], v[40:41] op_sel_hi:[1,0]
	v_pk_mul_f32 v[102:103], v[102:103], v[40:41] op_sel_hi:[1,0]
	v_pk_mul_f32 v[100:101], v[68:69], v[100:101]
	v_pk_mul_f32 v[102:103], v[70:71], v[102:103]
	global_store_dwordx4 v[14:15], v[100:103], off offset:2048
	global_load_dwordx4 v[100:103], v[110:111], off offset:2048
	s_waitcnt vmcnt(15)
	v_pk_mul_f32 v[104:105], v[104:105], v[40:41] op_sel_hi:[1,0]
	v_pk_mul_f32 v[106:107], v[106:107], v[40:41] op_sel_hi:[1,0]
	v_pk_mul_f32 v[104:105], v[72:73], v[104:105]
	v_pk_mul_f32 v[106:107], v[74:75], v[106:107]
	global_store_dwordx4 v[14:15], v[104:107], off offset:3072
	global_load_dwordx4 v[104:107], v[110:111], off offset:3072
	v_mov_b32_e32 v14, v110
	v_mov_b32_e32 v15, v111
	s_andn2_b64 exec, exec, s[0:1]
	s_cbranch_execz .LBB0_2365
; __device__ __forceinline__ void final_phase(float* x, const float* ssq, const float* gn, bool team) {
;     ...
;     for (int m = mbeg; m < mend; m += mstep) { float s = ssq[(size_t)m * 32 + (lane & 31)];
; #pragma unroll
;         for (int o = 1; o < 32; o <<= 1) s += __shfl_xor(s, o);
;         const float rs = __builtin_amdgcn_rsqf(s * (1.0f / D) + 1e-6f); f32x4* xr = (f32x4*)(x + (size_t)m * D) + lane; const f32x4* gr = (const f32x4*)gn + lane;
; #pragma unroll
;         for (int j = 0; j < 8; ++j) xr[64 * j] = xr[64 * j] * rs * gr[64 * j]; }
.LBB0_2364:
	v_add_u32_e32 v0, v0, v2
	v_cmp_ge_i32_e32 vcc, v0, v22
	s_or_b64 s[0:1], vcc, s[0:1]
	s_nop 1
	v_cndmask_b32_e64 v108, v16, 0, vcc
	v_cndmask_b32_e64 v109, v17, 0, vcc
	v_cndmask_b32_e64 v112, v20, 0, vcc
	v_cndmask_b32_e64 v113, v21, 0, vcc
	v_lshl_add_u64 v[110:111], v[14:15], 0, v[108:109]
	v_lshl_add_u64 v[18:19], v[18:19], 0, v[112:113]
	s_waitcnt vmcnt(16)
	v_mov_b32_e32 v42, v3
	global_load_dword v3, v[18:19], off
	ds_bpermute_b32 v40, v23, v42
	s_waitcnt lgkmcnt(0)
	v_add_f32_e32 v42, v42, v40
	ds_bpermute_b32 v40, v24, v42
	s_waitcnt lgkmcnt(0)
	v_add_f32_e32 v42, v42, v40
	ds_bpermute_b32 v40, v25, v42
	s_waitcnt lgkmcnt(0)
	v_add_f32_e32 v42, v42, v40
	ds_bpermute_b32 v40, v26, v42
	s_waitcnt lgkmcnt(0)
	v_add_f32_e32 v42, v42, v40
	ds_bpermute_b32 v40, v27, v42
	s_waitcnt lgkmcnt(0)
	v_add_f32_e32 v42, v42, v40
	v_fmamk_f32 v42, v42, 0x3a000000, v1
	v_rsq_f32_e32 v40, v42
	s_waitcnt vmcnt(15)
	v_pk_mul_f32 v[76:77], v[76:77], v[40:41] op_sel_hi:[1,0]
	v_pk_mul_f32 v[78:79], v[78:79], v[40:41] op_sel_hi:[1,0]
	v_pk_mul_f32 v[76:77], v[44:45], v[76:77]
	v_pk_mul_f32 v[78:79], v[46:47], v[78:79]
	global_store_dwordx4 v[14:15], v[76:79], off offset:-4096
	global_load_dwordx4 v[76:79], v[110:111], off offset:-4096
	s_waitcnt vmcnt(15)
	v_pk_mul_f32 v[80:81], v[80:81], v[40:41] op_sel_hi:[1,0]
	v_pk_mul_f32 v[82:83], v[82:83], v[40:41] op_sel_hi:[1,0]
	v_pk_mul_f32 v[80:81], v[48:49], v[80:81]
	v_pk_mul_f32 v[82:83], v[50:51], v[82:83]
	global_store_dwordx4 v[14:15], v[80:83], off offset:-3072
	global_load_dwordx4 v[80:83], v[110:111], off offset:-3072
	s_waitcnt vmcnt(15)
	v_pk_mul_f32 v[84:85], v[84:85], v[40:41] op_sel_hi:[1,0]
	v_pk_mul_f32 v[86:87], v[86:87], v[40:41] op_sel_hi:[1,0]
	v_pk_mul_f32 v[84:85], v[52:53], v[84:85]
	v_pk_mul_f32 v[86:87], v[54:55], v[86:87]
	global_store_dwordx4 v[14:15], v[84:87], off offset:-2048
	global_load_dwordx4 v[84:87], v[110:111], off offset:-2048
	s_waitcnt vmcnt(15)
	v_pk_mul_f32 v[88:89], v[88:89], v[40:41] op_sel_hi:[1,0]
	v_pk_mul_f32 v[90:91], v[90:91], v[40:41] op_sel_hi:[1,0]
	v_pk_mul_f32 v[88:89], v[56:57], v[88:89]
	v_pk_mul_f32 v[90:91], v[58:59], v[90:91]
	global_store_dwordx4 v[14:15], v[88:91], off offset:-1024
	global_load_dwordx4 v[88:91], v[110:111], off offset:-1024
	s_waitcnt vmcnt(15)
	v_pk_mul_f32 v[92:93], v[92:93], v[40:41] op_sel_hi:[1,0]
	v_pk_mul_f32 v[94:95], v[94:95], v[40:41] op_sel_hi:[1,0]
	v_pk_mul_f32 v[92:93], v[60:61], v[92:93]
	v_pk_mul_f32 v[94:95], v[62:63], v[94:95]
	global_store_dwordx4 v[14:15], v[92:95], off
	global_load_dwordx4 v[92:95], v[110:111], off
	s_waitcnt vmcnt(15)
	v_pk_mul_f32 v[96:97], v[96:97], v[40:41] op_sel_hi:[1,0]
	v_pk_mul_f32 v[98:99], v[98:99], v[40:41] op_sel_hi:[1,0]
	v_pk_mul_f32 v[96:97], v[64:65], v[96:97]
	v_pk_mul_f32 v[98:99], v[66:67], v[98:99]
	global_store_dwordx4 v[14:15], v[96:99], off offset:1024
	global_load_dwordx4 v[96:99], v[110:111], off offset:1024
	s_waitcnt vmcnt(15)
	v_pk_mul_f32 v[100:101], v[100:101], v[40:41] op_sel_hi:[1,0]
	v_pk_mul_f32 v[102:103], v[102:103], v[40:41] op_sel_hi:[1,0]
	v_pk_mul_f32 v[100:101], v[68:69], v[100:101]
	v_pk_mul_f32 v[102:103], v[70:71], v[102:103]
	global_store_dwordx4 v[14:15], v[100:103], off offset:2048
	global_load_dwordx4 v[100:103], v[110:111], off offset:2048
	s_waitcnt vmcnt(15)
	v_pk_mul_f32 v[104:105], v[104:105], v[40:41] op_sel_hi:[1,0]
	v_pk_mul_f32 v[106:107], v[106:107], v[40:41] op_sel_hi:[1,0]
	v_pk_mul_f32 v[104:105], v[72:73], v[104:105]
	v_pk_mul_f32 v[106:107], v[74:75], v[106:107]
	global_store_dwordx4 v[14:15], v[104:107], off offset:3072
	global_load_dwordx4 v[104:107], v[110:111], off offset:3072
	v_mov_b32_e32 v14, v110
	v_mov_b32_e32 v15, v111
	s_andn2_b64 exec, exec, s[0:1]
	s_cbranch_execnz .LBB0_2364
.LBB0_2365:
	s_waitcnt vmcnt(0)
	s_endpgm
